# stagger: workgroups with blockIdx>=256 enter attention and ff1 phases half a step later (s_sleep)
# speedup vs baseline: 1.0047x; 1.0047x over previous
.LBB0_1003:
	s_cmpk_gt_i32 s74, 0x107f
	s_cbranch_scc1 .LBB0_1008
	s_cmpk_lt_u32 s74, 0x100
	s_cbranch_scc1 .Lstag9
	s_sleep 10
.Lstag9:
	v_lshrrev_b32_e32 v9, 3, v144
	v_xor_b32_e32 v2, v9, v144
	v_mul_u32_u24_e32 v0, 0x440, v9
	v_lshlrev_b32_e32 v64, 1, v0
	v_mov_b32_e32 v65, 0
	v_lshlrev_b32_e32 v2, 4, v2
	v_lshl_add_u64 v[0:1], s[94:95], 0, v[64:65]
	v_and_b32_e32 v2, 0x70, v2
	v_mov_b32_e32 v3, v65
	v_lshl_add_u64 v[0:1], v[0:1], 0, v[2:3]
	s_mov_b64 s[4:5], 0x2200000
	v_lshl_add_u64 v[66:67], v[0:1], 0, s[4:5]
	v_lshrrev_b32_e32 v0, 2, v144
	v_lshrrev_b32_e32 v1, 5, v144
	v_and_b32_e32 v0, 24, v0
	v_and_b32_e32 v1, 28, v1
	v_add_u32_e32 v0, v0, v1
	v_and_or_b32 v0, v9, 3, v0
	v_mul_u32_u24_e32 v0, 0x440, v0
	v_lshlrev_b32_e32 v0, 1, v0
	v_mov_b32_e32 v1, v65
	v_lshl_add_u64 v[4:5], s[94:95], 0, v[0:1]
	v_lshl_add_u64 v[2:3], v[4:5], 0, v[2:3]
	s_mov_b64 s[4:5], 0x1090000
	v_lshrrev_b32_e32 v6, 4, v144
	v_bfe_u32 v7, v144, 4, 2
	v_and_b32_e32 v8, 15, v144
	v_lshl_add_u64 v[68:69], v[2:3], 0, s[4:5]
	v_and_b32_e32 v1, 7, v144
	v_lshrrev_b32_e32 v2, 1, v144
	s_movk_i32 s4, 0x1e0
	v_and_or_b32 v79, v2, s4, v8
	v_bitop3_b32 v2, v6, v1, 3 bitop3:0x6c
	v_bitop3_b32 v1, v7, v1, 4 bitop3:0x36
	v_lshlrev_b32_e32 v83, 4, v1
	s_waitcnt lgkmcnt(0)
	s_load_dword s28, s[78:79], 0xc8
	v_bitop3_b32 v1, v9, 7, v144 bitop3:0x48
	v_lshlrev_b32_e32 v1, 4, v1
	v_lshlrev_b32_e32 v78, 4, v144
	v_or_b32_e32 v64, v1, v64
	s_add_u32 s0, s94, 0x4510000
	v_lshlrev_b32_e32 v81, 4, v2
	v_lshlrev_b32_e32 v2, 3, v7
	v_lshl_add_u64 v[70:71], s[94:95], 0, v[64:65]
	v_or_b32_e32 v64, v0, v1
	v_add_u32_e32 v86, 0, v78
	s_addc_u32 s1, s95, 0
	v_lshlrev_b32_e32 v80, 7, v8
	v_lshlrev_b32_e32 v82, 7, v79
	v_or_b32_e32 v84, 16, v79
	v_lshl_add_u64 v[72:73], s[94:95], 0, v[64:65]
	s_movk_i32 s29, 0x211
	v_mov_b32_e32 v85, 0x44000
	v_add_u32_e32 v87, 0x4000, v86
	s_mov_b64 s[4:5], 0x11000
	v_add_u32_e32 v88, 0x1000, v86
	v_add_u32_e32 v89, 0x5000, v86
	s_mov_b64 s[6:7], 0x22000
	v_add_u32_e32 v90, 0x2000, v86
	v_add_u32_e32 v91, 0x6000, v86
	s_mov_b64 s[8:9], 0x33000
	v_add_u32_e32 v92, 0x3000, v86
	v_add_u32_e32 v93, 0x7000, v86
	s_mov_b64 s[10:11], 0x2200080
	s_mov_b64 s[12:13], 0x1090080
	s_mov_b64 s[14:15], 0x2211080
	s_mov_b64 s[16:17], 0x10a1080
	s_mov_b64 s[18:19], 0x2222080
	s_mov_b64 s[20:21], 0x10b2080
	s_mov_b64 s[22:23], 0x2233080
	s_mov_b64 s[24:25], 0x10c3080
	s_movk_i32 s30, 0x2080
	v_lshlrev_b32_e32 v64, 1, v2
	s_mov_b32 s31, s74

.LBB0_1471:
	s_cmpk_gt_i32 s74, 0x5ff
	s_cbranch_scc1 .LBB0_1485
	s_cmpk_lt_u32 s74, 0x100
	s_cbranch_scc1 .Lstag13
	s_sleep 16
.Lstag13:
	s_waitcnt lgkmcnt(0)
	s_load_dword s18, s[78:79], 0xc8
	s_add_u32 s16, s94, 0x4510000
	s_addc_u32 s17, s95, 0
	s_add_u32 s19, s94, 0x5dd0000
	s_addc_u32 s20, s95, 0
	s_waitcnt lgkmcnt(0)
	v_cvt_f32_u32_e32 v0, s18
	s_add_u32 s21, s94, 0x7690000
	s_addc_u32 s22, s95, 0
	s_add_u32 s23, s94, 0x9fd0000
	v_rcp_iflag_f32_e32 v0, v0
	s_addc_u32 s24, s95, 0
	s_sub_i32 s2, 0, s18
	v_lshrrev_b32_e32 v7, 6, v144
	v_mul_f32_e32 v0, 0x4f7ffffe, v0
	v_cvt_u32_f32_e32 v0, v0
	v_and_b32_e32 v5, 31, v144
	v_lshlrev_b32_e32 v9, 5, v7
	v_or_b32_e32 v145, v9, v5
	v_readfirstlane_b32 s3, v0
	s_mul_i32 s2, s2, s3
	s_mul_hi_u32 s2, s3, s2
	s_add_i32 s25, s3, s2
	s_mul_hi_u32 s2, s25, 0x600
	s_mul_i32 s2, s2, s18
	s_sub_i32 s2, 0x600, s2
	s_sub_i32 s3, s2, s18
	s_cmp_ge_u32 s2, s18
	s_cselect_b32 s2, s3, s2
	s_sub_i32 s3, s2, s18
	s_cmp_ge_u32 s2, s18
	s_cselect_b32 s2, s3, s2
	s_and_b32 s3, s18, 1
	s_or_b32 s2, s3, s2
	s_cmp_lg_u32 s2, 0
	s_cselect_b64 s[2:3], -1, 0
	s_lshr_b32 s27, s18, 1
	v_lshl_add_u32 v209, v5, 7, 0
	v_cvt_f32_u32_e32 v5, s27
	v_bfe_u32 v11, v144, 3, 3
	v_lshlrev_b32_e32 v10, 4, v7
	v_lshlrev_b32_e32 v203, 11, v7
	v_rcp_iflag_f32_e32 v5, v5
	v_lshlrev_b32_e32 v205, 12, v7
	v_or_b32_e32 v7, 8, v9
	v_lshrrev_b32_e32 v4, 2, v144
	v_or_b32_e32 v14, 8, v10
	v_or_b32_e32 v18, v7, v11
	v_lshlrev_b32_e32 v206, 7, v7
	v_or_b32_e32 v7, 16, v9
	v_mul_f32_e32 v5, 0x4f7ffffe, v5
	v_bfe_u32 v3, v144, 5, 1
	v_lshrrev_b32_e32 v13, 1, v144
	v_and_b32_e32 v12, 8, v4
	s_movk_i32 s6, 0xf3
	v_or_b32_e32 v16, v14, v11
	v_or_b32_e32 v20, v7, v11
	v_lshlrev_b32_e32 v207, 7, v7
	v_or_b32_e32 v7, 24, v9
	v_cvt_u32_f32_e32 v5, v5
	v_bfe_u32 v15, v144, 1, 3
	v_and_or_b32 v19, v16, s6, v12
	v_lshrrev_b32_e32 v21, 1, v16
	v_or_b32_e32 v16, v9, v11
	v_or_b32_e32 v9, v7, v11
	v_lshlrev_b32_e32 v208, 7, v7
	v_bitop3_b32 v7, v3, v13, 7 bitop3:0x78
	v_and_b32_e32 v1, 63, v144
	v_lshlrev_b32_e32 v210, 4, v7
	v_bitop3_b32 v7, v3, v15, 2 bitop3:0x36
	v_lshlrev_b32_e32 v2, 3, v3
	v_lshl_add_u32 v202, v1, 4, 0
	v_lshlrev_b32_e32 v4, 2, v3
	v_or_b32_e32 v1, v10, v11
	v_lshlrev_b32_e32 v211, 4, v7
	v_bitop3_b32 v7, v3, v15, 4 bitop3:0x36
	v_bitop3_b32 v3, v3, v15, 6 bitop3:0x36
	v_and_or_b32 v17, v1, s6, v12
	v_lshlrev_b32_e32 v213, 4, v3
	s_sub_i32 s6, 0, s27
	v_readfirstlane_b32 s7, v5
	v_bitop3_b32 v3, v21, 7, v144 bitop3:0x48
	v_mul_u32_u24_e32 v5, 0x600, v19
	v_lshlrev_b32_e32 v204, 7, v14
	v_mul_u32_u24_e32 v14, 0x2100, v16
	v_lshrrev_b32_e32 v23, 1, v16
	s_mul_i32 s6, s6, s7
	v_lshl_or_b32 v3, v3, 4, v5
	s_mov_b64 s[4:5], 0x5dd0000
	v_mov_b32_e32 v147, 0
	v_mul_u32_u24_e32 v148, 0x2100, v18
	v_lshrrev_b32_e32 v24, 1, v18
	s_mul_hi_u32 s6, s7, s6
	v_add_u32_e32 v146, 0x31800, v3
	v_bitop3_b32 v3, v23, 7, v144 bitop3:0x48
	v_lshlrev_b32_e32 v5, 1, v14
	v_mul_u32_u24_e32 v150, 0x2100, v20
	v_lshrrev_b32_e32 v25, 1, v20
	s_add_i32 s28, s7, s6
	v_lshl_add_u64 v[154:155], v[146:147], 0, s[4:5]
	v_lshl_or_b32 v146, v3, 4, v5
	s_mov_b64 s[6:7], 0x7690100
	v_bitop3_b32 v3, v24, 7, v144 bitop3:0x48
	v_lshlrev_b32_e32 v5, 1, v148
	v_mul_u32_u24_e32 v152, 0x2100, v9
	v_lshrrev_b32_e32 v9, 1, v9
	v_lshl_add_u64 v[156:157], v[146:147], 0, s[6:7]
	v_lshl_or_b32 v146, v3, 4, v5
	v_bitop3_b32 v3, v25, 7, v144 bitop3:0x48
	v_lshlrev_b32_e32 v5, 1, v150
	v_lshrrev_b32_e32 v1, 1, v1
	v_lshl_add_u64 v[158:159], v[146:147], 0, s[6:7]
	v_lshl_or_b32 v146, v3, 4, v5
	v_bitop3_b32 v3, v9, 7, v144 bitop3:0x48
	v_lshlrev_b32_e32 v5, 1, v152
	v_xor_b32_e32 v8, v1, v144
	v_xor_b32_e32 v12, v21, v144
	v_xor_b32_e32 v16, v23, v144
	v_xor_b32_e32 v18, v24, v144
	v_xor_b32_e32 v20, v25, v144
	v_xor_b32_e32 v11, v9, v144
	v_lshl_add_u64 v[160:161], v[146:147], 0, s[6:7]
	v_lshl_or_b32 v146, v3, 4, v5
	v_bitop3_b32 v1, v1, 7, v144 bitop3:0x48
	v_mul_u32_u24_e32 v3, 0x600, v17
	v_lshlrev_b32_e32 v8, 3, v8
	v_lshlrev_b32_e32 v12, 3, v12
	v_lshlrev_b32_e32 v16, 3, v16
	v_lshlrev_b32_e32 v18, 3, v18
	v_lshlrev_b32_e32 v20, 3, v20
	v_lshlrev_b32_e32 v11, 3, v11
	v_lshl_or_b32 v1, v1, 4, v3
	v_mul_u32_u24_e32 v0, 0x300, v145
	v_mul_u32_u24_e32 v6, 0x300, v17
	v_and_b32_e32 v8, 56, v8
	v_mul_u32_u24_e32 v10, 0x300, v19
	v_and_b32_e32 v12, 56, v12
	v_and_b32_e32 v16, 56, v16
	v_and_b32_e32 v18, 56, v18
	v_and_b32_e32 v20, 56, v20
	v_and_b32_e32 v22, 56, v11
	v_lshl_add_u64 v[162:163], v[146:147], 0, s[6:7]
	v_add_u32_e32 v146, 0x30000, v1
	s_movk_i32 s26, 0x600
	v_mov_b32_e32 v149, v147
	v_mov_b32_e32 v151, v147
	v_mov_b32_e32 v153, v147
	v_lshlrev_b32_e32 v212, 4, v7
	v_lshl_add_u64 v[164:165], v[146:147], 0, s[4:5]
	s_mov_b64 s[4:5], 0x1800
	s_movk_i32 s29, 0x2000
	s_mov_b64 s[6:7], 0x18000
	s_mov_b64 s[8:9], 0x19800
	s_mov_b64 s[10:11], 0x80
	v_lshlrev_b32_e32 v146, 1, v4
	v_lshlrev_b32_e32 v166, 1, v0
	v_lshlrev_b32_e32 v168, 1, v2
	v_lshlrev_b32_e32 v170, 1, v6
	v_lshlrev_b32_e32 v172, 1, v8
	v_lshlrev_b32_e32 v174, 1, v10
	v_lshlrev_b32_e32 v176, 1, v12
	v_lshlrev_b32_e32 v178, 1, v14
	v_lshlrev_b32_e32 v180, 1, v16
	v_lshlrev_b32_e32 v182, 1, v18
	v_lshlrev_b32_e32 v184, 1, v20
	v_lshlrev_b32_e32 v186, 1, v22
	v_mov_b32_e32 v214, 0x4200
	s_mov_b32 s30, s74
	s_branch .LBB0_1474
